# GLA pass C: next item's ten tile loads prefetched during the current item (software pipelining), norm-gain loads issued ahead of them
# baseline (speedup 1.0000x reference)
.LBB0_502:
	s_cmp_lt_i32 s76, 6
	s_cselect_b64 s[0:1], -1, 0
	s_and_b64 s[42:43], s[0:1], s[2:3]
	s_xor_b64 s[0:1], s[42:43], -1
	s_cmpk_gt_i32 s33, 0x7ff
	s_cselect_b64 s[2:3], -1, 0
	s_or_b64 s[0:1], s[0:1], s[2:3]
	s_and_b64 vcc, exec, s[0:1]
	s_cbranch_vccnz .LBB0_517
	s_add_u32 s2, s74, 0xe285000
	s_addc_u32 s3, s75, 0
	s_add_u32 s0, s74, 0xa085000
	s_addc_u32 s1, s75, 0
	s_add_u32 s38, s74, 0x1e85000
	s_addc_u32 s39, s75, 0
	s_add_u32 s44, s74, 0x6085000
	v_mbcnt_lo_u32_b32 v0, -1, 0
	s_addc_u32 s45, s75, 0
	s_mov_b32 s47, 0
	v_mov_b32_e32 v53, 0
	s_add_i32 s50, 0, 0x10000
	s_add_i32 s51, 0, 0x15000
	s_movk_i32 s52, 0x1a00
	v_mov_b64_e32 v[54:55], s[2:3]
	s_movk_i32 s53, 0x140
	s_movk_i32 s54, 0x90
	s_movk_i32 s55, 0x2000
	s_movk_i32 s56, 0x4000
	s_movk_i32 s57, 0x6000
	v_mov_b32_e32 v66, 0x358637bd
	s_mov_b32 s58, 0x800000
	v_mbcnt_hi_u32_b32 v67, -1, v0
	s_mov_b32 s59, s33
	s_mov_b32 s32, s59
	v_mov_b32_e32 v195, 0
	s_ashr_i32 s2, s32, 9
	s_bfe_u32 s62, s32, 0x20007
	s_and_b32 s6, s32, 0x7f
	s_lshl_b32 s3, s2, 13
	s_lshl_b32 s2, s2, 2
	s_lshl_b32 s4, s6, 6
	s_or_b32 s7, s2, s62
	s_or_b32 s8, s4, s3
	s_lshl_b32 s4, s7, 1
	s_add_i32 s2, s6, 4
	s_sub_i32 s5, 0x83, s6
	s_mul_i32 s3, s7, 0x108
	s_mul_hi_i32 s9, s4, 0x84
	s_add_u32 s2, s3, s2
	s_addc_u32 s3, s9, 0
	s_lshl_b64 s[2:3], s[2:3], 14
	s_add_u32 s2, s0, s2
	s_addc_u32 s3, s1, s3
	s_or_b32 s4, s4, 1
	s_mul_hi_i32 s9, s4, 0x84
	s_mulk_i32 s4, 0x84
	s_add_u32 s4, s4, s5
	v_mov_b32_e32 v196, v188
	s_addc_u32 s5, s9, 0
	s_lshl_b64 s[4:5], s[4:5], 14
	v_lshlrev_b32_e32 v168, 4, v196
	v_ashrrev_i32_e32 v187, 4, v196
	s_add_u32 s4, s0, s4
	v_and_b32_e32 v194, 0xf0, v168
	v_add_u32_e32 v140, s8, v187
	s_addc_u32 s5, s1, s5
	v_lshl_add_u64 v[156:157], s[2:3], 0, v[194:195]
	v_mad_i64_i32 v[140:141], s[2:3], v140, s52, v[54:55]
	s_lshl_b32 s46, s62, 8
	v_lshl_add_u64 v[140:141], v[140:141], 0, s[46:47]
	v_lshl_add_u64 v[148:149], v[140:141], 0, v[194:195]
	v_lshlrev_b32_e32 v140, 7, v187
	v_ashrrev_i32_e32 v141, 31, v140
	v_lshlrev_b64 v[150:151], 1, v[140:141]
	v_lshl_add_u64 v[152:153], v[156:157], 0, v[150:151]
	global_load_dwordx4 v[140:143], v[148:149], off offset:1024
	global_load_dwordx4 v[144:147], v[152:153], off
	v_add_u32_e32 v148, 0x200, v196
	v_ashrrev_i32_e32 v192, 4, v148
	v_add_u32_e32 v148, s8, v192
	v_lshl_add_u64 v[158:159], s[4:5], 0, v[194:195]
	v_mad_i64_i32 v[148:149], s[2:3], v148, s52, v[54:55]
	v_lshl_add_u64 v[160:161], v[158:159], 0, v[150:151]
	v_lshl_add_u64 v[148:149], v[148:149], 0, s[46:47]
	s_lshl_b32 s7, s7, 7
	v_lshl_add_u64 v[162:163], v[148:149], 0, v[194:195]
	global_load_dwordx4 v[148:151], v[160:161], off
	global_load_dwordx4 v[152:155], v[162:163], off offset:1024
	v_lshlrev_b32_e32 v160, 7, v192
	s_or_b32 s6, s7, s6
	v_ashrrev_i32_e32 v161, 31, v160
	s_ashr_i32 s7, s6, 31
	v_lshlrev_b64 v[160:161], 1, v[160:161]
	s_lshl_b64 s[6:7], s[6:7], 15
	v_lshl_add_u64 v[164:165], v[156:157], 0, v[160:161]
	v_ashrrev_i32_e32 v193, 3, v196
	v_lshl_add_u64 v[166:167], v[158:159], 0, v[160:161]
	global_load_dwordx4 v[156:159], v[164:165], off
	global_load_dwordx4 v[160:163], v[166:167], off
	s_add_u32 s2, s38, s6
	v_lshlrev_b32_e32 v164, 6, v193
	s_addc_u32 s3, s39, s7
	v_ashrrev_i32_e32 v165, 31, v164
	v_add_u32_e32 v184, 0, v194
	v_add_u32_e32 v185, s50, v194
	v_add_u32_e32 v186, s51, v194
	v_lshl_add_u64 v[164:165], v[164:165], 1, s[2:3]
	v_and_b32_e32 v194, 0x70, v168
	v_lshl_add_u64 v[172:173], v[164:165], 0, v[194:195]
	v_add_co_u32_e32 v174, vcc, s55, v172
	v_readfirstlane_b32 s63, v196
	s_nop 0
	v_addc_co_u32_e32 v175, vcc, 0, v173, vcc
	global_load_dwordx4 v[164:167], v[172:173], off
	global_load_dwordx4 v[168:171], v[174:175], off
	v_add_co_u32_e32 v180, vcc, s56, v172
	v_and_b32_e32 v197, 31, v196
	s_nop 0
	v_addc_co_u32_e32 v181, vcc, 0, v173, vcc
	v_add_co_u32_e32 v182, vcc, s57, v172
	s_bfe_u32 s64, s63, 0x10006
	s_nop 0
	v_addc_co_u32_e32 v183, vcc, 0, v173, vcc
	global_load_dwordx4 v[172:175], v[180:181], off
	global_load_dwordx4 v[176:179], v[182:183], off
	s_branch .LBB0_505
.LBB0_504:
	s_or_b64 exec, exec, s[2:3]
	v_or_b32_e32 v20, s48, v52
	v_ashrrev_i32_e32 v21, 31, v20
	v_lshl_add_u64 v[22:23], v[20:21], 2, s[60:61]
	s_waitcnt lgkmcnt(0)
	s_barrier
	s_add_i32 s2, s5, 0
	s_waitcnt vmcnt(10)
	v_lshlrev_b32_e32 v24, 16, v64
	v_and_b32_e32 v25, 0xffff0000, v64
	v_lshlrev_b32_e32 v26, 16, v65
	v_and_b32_e32 v27, 0xffff0000, v65
	v_lshl_add_u32 v30, v68, 2, s2
	v_mul_f32_e32 v31, 0xbfb8aa3b, v24
	v_mul_f32_e32 v32, 0xbfb8aa3b, v25
	v_mul_f32_e32 v33, 0xbfb8aa3b, v26
	v_mul_f32_e32 v34, 0xbfb8aa3b, v27
	v_add_u32_e32 v35, 0x1a000, v30
	v_exp_f32_e32 v36, v31
	v_exp_f32_e32 v37, v32
	v_exp_f32_e32 v38, v33
	v_exp_f32_e32 v34, v34
	ds_read2_b32 v[30:31], v35 offset1:32
	ds_read2_b32 v[32:33], v35 offset0:64 offset1:96
	v_add_f32_e32 v35, 1.0, v36
	v_add_f32_e32 v36, 1.0, v37
	v_add_f32_e32 v37, 1.0, v38
	v_add_f32_e32 v38, 1.0, v34
	v_rcp_f32_e32 v34, v35
	v_rcp_f32_e32 v35, v36
	v_rcp_f32_e32 v36, v37
	v_rcp_f32_e32 v37, v38
	s_waitcnt lgkmcnt(1)
	v_mov_b32_e32 v38, v30
	s_waitcnt lgkmcnt(0)
	v_mov_b32_e32 v39, v32
	v_mov_b32_e32 v32, v31
	v_pk_add_f32 v[30:31], v[38:39], v[32:33]
	v_ashrrev_i32_e32 v63, 31, v62
	v_add_f32_e32 v30, v30, v31
	v_fmamk_f32 v30, v30, 0x3c000000, v66
	v_mul_f32_e32 v31, 0x4b800000, v30
	v_cmp_gt_f32_e32 vcc, s58, v30
	v_lshlrev_b64 v[28:29], 11, v[62:63]
	s_lshl_b32 s46, s4, 1
	v_cndmask_b32_e32 v30, v30, v31, vcc
	v_rsq_f32_e32 v30, v30
	v_lshl_add_u64 v[28:29], s[44:45], 0, v[28:29]
	v_lshl_add_u64 v[28:29], v[28:29], 0, s[46:47]
	v_lshl_add_u64 v[20:21], v[20:21], 1, v[28:29]
	v_and_b32_e32 v120, 32, v188
	v_lshrrev_b32_e32 v120, 2, v120
	v_mov_b32_e32 v121, 0
	v_lshl_add_u64 v[122:123], v[20:21], 0, v[120:121]
	v_mul_f32_e32 v28, 0x45800000, v30
	v_cndmask_b32_e32 v28, v30, v28, vcc
	v_pk_mul_f32 v[0:1], v[0:1], v[28:29] op_sel_hi:[1,0]
	v_pk_mul_f32 v[2:3], v[2:3], v[28:29] op_sel_hi:[1,0]
	v_pk_mul_f32 v[24:25], v[34:35], v[24:25]
	v_pk_mul_f32 v[26:27], v[36:37], v[26:27]
	v_pk_mul_f32 v[4:5], v[4:5], v[28:29] op_sel_hi:[1,0]
	v_pk_mul_f32 v[6:7], v[6:7], v[28:29] op_sel_hi:[1,0]
	v_pk_mul_f32 v[8:9], v[8:9], v[28:29] op_sel_hi:[1,0]
	v_pk_mul_f32 v[10:11], v[10:11], v[28:29] op_sel_hi:[1,0]
	s_add_i32 s59, s59, s78
	s_cmpk_lt_i32 s59, 0x800
	v_pk_mul_f32 v[0:1], v[124:125], v[0:1]
	v_pk_mul_f32 v[2:3], v[126:127], v[2:3]
	v_pk_mul_f32 v[0:1], v[24:25], v[0:1]
	v_pk_mul_f32 v[2:3], v[26:27], v[2:3]
	v_cvt_pk_bf16_f32 v112, v0, v1
	v_cvt_pk_bf16_f32 v113, v2, v3
	v_lshlrev_b32_e32 v16, 16, v60
	v_and_b32_e32 v17, 0xffff0000, v60
	v_lshlrev_b32_e32 v18, 16, v61
	v_and_b32_e32 v19, 0xffff0000, v61
	v_mul_f32_e32 v24, 0xbfb8aa3b, v16
	v_mul_f32_e32 v25, 0xbfb8aa3b, v17
	v_mul_f32_e32 v26, 0xbfb8aa3b, v18
	v_mul_f32_e32 v27, 0xbfb8aa3b, v19
	v_exp_f32_e32 v24, v24
	v_exp_f32_e32 v25, v25
	v_exp_f32_e32 v26, v26
	v_exp_f32_e32 v27, v27
	v_add_f32_e32 v24, 1.0, v24
	v_add_f32_e32 v25, 1.0, v25
	v_add_f32_e32 v26, 1.0, v26
	v_add_f32_e32 v27, 1.0, v27
	v_rcp_f32_e32 v24, v24
	v_rcp_f32_e32 v25, v25
	v_rcp_f32_e32 v26, v26
	v_rcp_f32_e32 v27, v27
	v_pk_mul_f32 v[16:17], v[24:25], v[16:17]
	v_pk_mul_f32 v[18:19], v[26:27], v[18:19]
	v_pk_mul_f32 v[0:1], v[100:101], v[4:5]
	v_pk_mul_f32 v[2:3], v[102:103], v[6:7]
	v_pk_mul_f32 v[0:1], v[16:17], v[0:1]
	v_pk_mul_f32 v[2:3], v[18:19], v[2:3]
	v_cvt_pk_bf16_f32 v114, v0, v1
	v_cvt_pk_bf16_f32 v115, v2, v3
	s_nop 1
	v_permlane32_swap_b32_e32 v112, v114
	v_permlane32_swap_b32_e32 v113, v115
	global_store_dwordx4 v[122:123], v[112:115], off
	v_lshlrev_b32_e32 v4, 16, v58
	v_and_b32_e32 v5, 0xffff0000, v58
	v_lshlrev_b32_e32 v6, 16, v59
	v_and_b32_e32 v7, 0xffff0000, v59
	v_mul_f32_e32 v16, 0xbfb8aa3b, v4
	v_mul_f32_e32 v17, 0xbfb8aa3b, v5
	v_mul_f32_e32 v18, 0xbfb8aa3b, v6
	v_mul_f32_e32 v19, 0xbfb8aa3b, v7
	v_exp_f32_e32 v16, v16
	v_exp_f32_e32 v17, v17
	v_exp_f32_e32 v18, v18
	v_exp_f32_e32 v19, v19
	v_add_f32_e32 v16, 1.0, v16
	v_add_f32_e32 v17, 1.0, v17
	v_add_f32_e32 v18, 1.0, v18
	v_add_f32_e32 v19, 1.0, v19
	v_rcp_f32_e32 v16, v16
	v_rcp_f32_e32 v17, v17
	v_rcp_f32_e32 v18, v18
	v_rcp_f32_e32 v19, v19
	v_pk_mul_f32 v[4:5], v[16:17], v[4:5]
	v_pk_mul_f32 v[6:7], v[18:19], v[6:7]
	v_pk_mul_f32 v[0:1], v[104:105], v[8:9]
	v_pk_mul_f32 v[2:3], v[106:107], v[10:11]
	v_pk_mul_f32 v[0:1], v[4:5], v[0:1]
	v_pk_mul_f32 v[2:3], v[6:7], v[2:3]
	v_cvt_pk_bf16_f32 v116, v0, v1
	v_cvt_pk_bf16_f32 v117, v2, v3
	v_lshlrev_b32_e32 v4, 16, v56
	v_and_b32_e32 v5, 0xffff0000, v56
	v_lshlrev_b32_e32 v6, 16, v57
	v_and_b32_e32 v7, 0xffff0000, v57
	v_mul_f32_e32 v8, 0xbfb8aa3b, v4
	v_mul_f32_e32 v9, 0xbfb8aa3b, v5
	v_mul_f32_e32 v10, 0xbfb8aa3b, v6
	v_mul_f32_e32 v11, 0xbfb8aa3b, v7
	v_exp_f32_e32 v8, v8
	v_exp_f32_e32 v9, v9
	v_exp_f32_e32 v10, v10
	v_exp_f32_e32 v11, v11
	v_add_f32_e32 v8, 1.0, v8
	v_add_f32_e32 v9, 1.0, v9
	v_add_f32_e32 v10, 1.0, v10
	v_add_f32_e32 v11, 1.0, v11
	v_rcp_f32_e32 v8, v8
	v_rcp_f32_e32 v9, v9
	v_rcp_f32_e32 v10, v10
	v_rcp_f32_e32 v11, v11
	v_pk_mul_f32 v[4:5], v[8:9], v[4:5]
	v_pk_mul_f32 v[8:9], v[12:13], v[28:29] op_sel_hi:[1,0]
	v_pk_mul_f32 v[6:7], v[10:11], v[6:7]
	v_pk_mul_f32 v[10:11], v[14:15], v[28:29] op_sel_hi:[1,0]
	v_pk_mul_f32 v[0:1], v[108:109], v[8:9]
	v_pk_mul_f32 v[2:3], v[110:111], v[10:11]
	v_pk_mul_f32 v[0:1], v[4:5], v[0:1]
	v_pk_mul_f32 v[2:3], v[6:7], v[2:3]
	v_cvt_pk_bf16_f32 v118, v0, v1
	v_cvt_pk_bf16_f32 v119, v2, v3
	s_nop 1
	v_permlane32_swap_b32_e32 v116, v118
	v_permlane32_swap_b32_e32 v117, v119
	global_store_dwordx4 v[122:123], v[116:119], off offset:32
	s_barrier
	s_cbranch_scc0 .LBB0_517
.LBB0_505:
	s_ashr_i32 s2, s59, 9
	s_bfe_u32 s62, s59, 0x20007
	s_and_b32 s6, s59, 0x7f
	s_lshl_b32 s3, s2, 13
	s_lshl_b32 s2, s2, 2
	s_lshl_b32 s4, s6, 6
	s_or_b32 s7, s2, s62
	s_or_b32 s8, s4, s3
	s_lshl_b32 s4, s7, 1
	s_add_i32 s2, s6, 4
	s_sub_i32 s5, 0x83, s6
	s_mul_i32 s3, s7, 0x108
	s_mul_hi_i32 s9, s4, 0x84
	s_add_u32 s2, s3, s2
	s_addc_u32 s3, s9, 0
	s_lshl_b64 s[2:3], s[2:3], 14
	s_add_u32 s2, s0, s2
	s_addc_u32 s3, s1, s3
	s_or_b32 s4, s4, 1
	s_mul_hi_i32 s9, s4, 0x84
	s_mulk_i32 s4, 0x84
	s_add_u32 s4, s4, s5
	v_mov_b32_e32 v63, v188
	s_addc_u32 s5, s9, 0
	s_lshl_b64 s[4:5], s[4:5], 14
	v_lshlrev_b32_e32 v28, 4, v63
	v_ashrrev_i32_e32 v47, 4, v63
	s_add_u32 s4, s0, s4
	v_and_b32_e32 v52, 0xf0, v28
	v_add_u32_e32 v0, s8, v47
	s_addc_u32 s5, s1, s5
	v_lshl_add_u64 v[16:17], s[2:3], 0, v[52:53]
	v_mad_i64_i32 v[0:1], s[2:3], v0, s52, v[54:55]
	s_lshl_b32 s46, s62, 8
	v_lshl_add_u64 v[0:1], v[0:1], 0, s[46:47]
	v_lshl_add_u64 v[8:9], v[0:1], 0, v[52:53]
	v_lshlrev_b32_e32 v0, 7, v47
	v_ashrrev_i32_e32 v1, 31, v0
	v_lshlrev_b64 v[10:11], 1, v[0:1]
	v_lshl_add_u64 v[12:13], v[16:17], 0, v[10:11]
	v_add_u32_e32 v8, 0x200, v63
	v_ashrrev_i32_e32 v48, 4, v8
	v_add_u32_e32 v8, s8, v48
	v_lshl_add_u64 v[18:19], s[4:5], 0, v[52:53]
	v_mad_i64_i32 v[8:9], s[2:3], v8, s52, v[54:55]
	v_lshl_add_u64 v[20:21], v[18:19], 0, v[10:11]
	v_lshl_add_u64 v[8:9], v[8:9], 0, s[46:47]
	s_lshl_b32 s7, s7, 7
	v_lshl_add_u64 v[22:23], v[8:9], 0, v[52:53]
	v_lshlrev_b32_e32 v20, 7, v48
	s_or_b32 s6, s7, s6
	v_ashrrev_i32_e32 v21, 31, v20
	s_ashr_i32 s7, s6, 31
	v_lshlrev_b64 v[20:21], 1, v[20:21]
	s_lshl_b64 s[6:7], s[6:7], 15
	v_lshl_add_u64 v[24:25], v[16:17], 0, v[20:21]
	v_ashrrev_i32_e32 v49, 3, v63
	v_lshl_add_u64 v[26:27], v[18:19], 0, v[20:21]
	s_add_u32 s2, s38, s6
	v_lshlrev_b32_e32 v24, 6, v49
	s_addc_u32 s3, s39, s7
	v_ashrrev_i32_e32 v25, 31, v24
	v_add_u32_e32 v44, 0, v52
	v_add_u32_e32 v45, s50, v52
	v_add_u32_e32 v46, s51, v52
	v_lshl_add_u64 v[24:25], v[24:25], 1, s[2:3]
	v_and_b32_e32 v52, 0x70, v28
	v_lshl_add_u64 v[32:33], v[24:25], 0, v[52:53]
	v_add_co_u32_e32 v34, vcc, s55, v32
	v_readfirstlane_b32 s63, v63
	s_nop 0
	v_addc_co_u32_e32 v35, vcc, 0, v33, vcc
	v_add_co_u32_e32 v40, vcc, s56, v32
	v_and_b32_e32 v68, 31, v63
	s_nop 0
	v_addc_co_u32_e32 v41, vcc, 0, v33, vcc
	v_add_co_u32_e32 v42, vcc, s57, v32
	s_bfe_u32 s64, s63, 0x10006
	s_nop 0
	v_addc_co_u32_e32 v43, vcc, 0, v33, vcc
	v_mul_lo_u32 v40, v47, s53
	v_add_u32_e32 v41, v44, v40
	v_add_u32_e32 v42, v45, v40
	s_ashr_i32 s65, s63, 7
	s_lshl_b32 s48, s65, 5
	s_ashr_i32 s49, s48, 31
	s_bitcmp1_b32 s63, 6
	s_cselect_b64 s[36:37], -1, 0
	s_waitcnt vmcnt(0)
	ds_write_b128 v41, v[140:143] offset:45056
	ds_write_b128 v42, v[144:147]
	v_add_u32_e32 v0, v46, v40
	v_lshl_or_b32 v4, s64, 5, v68
	v_or_b32_e32 v62, s8, v4
	v_mad_u32_u24 v4, v4, s54, 0
	s_and_b64 vcc, exec, s[36:37]
	ds_write_b128 v0, v[148:151]
	v_mul_lo_u32 v0, v48, s53
	v_add_u32_e32 v1, v44, v0
	ds_write_b128 v1, v[152:155] offset:45056
	v_add_u32_e32 v1, v45, v0
	v_add_u32_e32 v0, v46, v0
	v_bfe_u32 v48, v63, 5, 1
	v_lshlrev_b32_e32 v5, 4, v48
	v_add_u32_e32 v87, v4, v5
	ds_write_b128 v1, v[156:159]
	ds_write_b128 v0, v[160:163]
	v_mul_lo_u32 v0, v49, s54
	v_add3_u32 v2, 0, v0, v52
	v_mad_i64_i32 v[0:1], s[2:3], v62, s52, v[54:55]
	v_lshl_add_u64 v[0:1], v[0:1], 0, s[46:47]
	v_lshl_add_u64 v[0:1], s[48:49], 1, v[0:1]
	v_lshlrev_b32_e32 v52, 3, v48
	ds_write_b128 v2, v[164:167] offset:8192
	ds_write_b128 v2, v[168:171] offset:17408
	v_lshl_add_u64 v[0:1], v[0:1], 0, v[52:53]
	global_load_dwordx2 v[64:65], v[0:1], off offset:2048
	global_load_dwordx2 v[60:61], v[0:1], off offset:2064
	global_load_dwordx2 v[58:59], v[0:1], off offset:2080
	global_load_dwordx2 v[56:57], v[0:1], off offset:2096
	v_lshl_or_b32 v128, v48, 2, s48
	v_lshlrev_b32_e32 v128, 2, v128
	global_load_dwordx4 v[124:127], v128, s[60:61]
	global_load_dwordx4 v[100:103], v128, s[60:61] offset:32
	global_load_dwordx4 v[104:107], v128, s[60:61] offset:64
	global_load_dwordx4 v[108:111], v128, s[60:61] offset:96
	v_add_u32_e32 v24, 0, v5
	v_mad_u32_u24 v25, v68, s54, v24
	ds_write_b128 v2, v[172:175] offset:26624
	ds_write_b128 v2, v[176:179] offset:35840
	s_waitcnt lgkmcnt(0)
	s_barrier
	v_writelane_b32 v198, s2, 0
	v_writelane_b32 v198, s3, 1
	v_writelane_b32 v198, s4, 2
	v_writelane_b32 v198, s5, 3
	v_writelane_b32 v198, s6, 4
	v_writelane_b32 v198, s7, 5
	v_writelane_b32 v198, s8, 6
	v_writelane_b32 v198, s9, 7
	v_writelane_b32 v198, s46, 8
	v_writelane_b32 v198, s62, 9
	v_writelane_b32 v198, s63, 10
	v_writelane_b32 v198, s64, 11
	s_add_i32 s32, s59, s78
	s_cmpk_lt_i32 s32, 0x800
	s_cselect_b32 s32, s32, s59
	v_mov_b32_e32 v195, 0
	s_ashr_i32 s2, s32, 9
	s_bfe_u32 s62, s32, 0x20007
	s_and_b32 s6, s32, 0x7f
	s_lshl_b32 s3, s2, 13
	s_lshl_b32 s2, s2, 2
	s_lshl_b32 s4, s6, 6
	s_or_b32 s7, s2, s62
	s_or_b32 s8, s4, s3
	s_lshl_b32 s4, s7, 1
	s_add_i32 s2, s6, 4
	s_sub_i32 s5, 0x83, s6
	s_mul_i32 s3, s7, 0x108
	s_mul_hi_i32 s9, s4, 0x84
	s_add_u32 s2, s3, s2
	s_addc_u32 s3, s9, 0
	s_lshl_b64 s[2:3], s[2:3], 14
	s_add_u32 s2, s0, s2
	s_addc_u32 s3, s1, s3
	s_or_b32 s4, s4, 1
	s_mul_hi_i32 s9, s4, 0x84
	s_mulk_i32 s4, 0x84
	s_add_u32 s4, s4, s5
	v_mov_b32_e32 v196, v188
	s_addc_u32 s5, s9, 0
	s_lshl_b64 s[4:5], s[4:5], 14
	v_lshlrev_b32_e32 v168, 4, v196
	v_ashrrev_i32_e32 v187, 4, v196
	s_add_u32 s4, s0, s4
	v_and_b32_e32 v194, 0xf0, v168
	v_add_u32_e32 v140, s8, v187
	s_addc_u32 s5, s1, s5
	v_lshl_add_u64 v[156:157], s[2:3], 0, v[194:195]
	v_mad_i64_i32 v[140:141], s[2:3], v140, s52, v[54:55]
	s_lshl_b32 s46, s62, 8
	v_lshl_add_u64 v[140:141], v[140:141], 0, s[46:47]
	v_lshl_add_u64 v[148:149], v[140:141], 0, v[194:195]
	v_lshlrev_b32_e32 v140, 7, v187
	v_ashrrev_i32_e32 v141, 31, v140
	v_lshlrev_b64 v[150:151], 1, v[140:141]
	v_lshl_add_u64 v[152:153], v[156:157], 0, v[150:151]
	global_load_dwordx4 v[140:143], v[148:149], off offset:1024
	global_load_dwordx4 v[144:147], v[152:153], off
	v_add_u32_e32 v148, 0x200, v196
	v_ashrrev_i32_e32 v192, 4, v148
	v_add_u32_e32 v148, s8, v192
	v_lshl_add_u64 v[158:159], s[4:5], 0, v[194:195]
	v_mad_i64_i32 v[148:149], s[2:3], v148, s52, v[54:55]
	v_lshl_add_u64 v[160:161], v[158:159], 0, v[150:151]
	v_lshl_add_u64 v[148:149], v[148:149], 0, s[46:47]
	s_lshl_b32 s7, s7, 7
	v_lshl_add_u64 v[162:163], v[148:149], 0, v[194:195]
	global_load_dwordx4 v[148:151], v[160:161], off
	global_load_dwordx4 v[152:155], v[162:163], off offset:1024
	v_lshlrev_b32_e32 v160, 7, v192
	s_or_b32 s6, s7, s6
	v_ashrrev_i32_e32 v161, 31, v160
	s_ashr_i32 s7, s6, 31
	v_lshlrev_b64 v[160:161], 1, v[160:161]
	s_lshl_b64 s[6:7], s[6:7], 15
	v_lshl_add_u64 v[164:165], v[156:157], 0, v[160:161]
	v_ashrrev_i32_e32 v193, 3, v196
	v_lshl_add_u64 v[166:167], v[158:159], 0, v[160:161]
	global_load_dwordx4 v[156:159], v[164:165], off
	global_load_dwordx4 v[160:163], v[166:167], off
	s_add_u32 s2, s38, s6
	v_lshlrev_b32_e32 v164, 6, v193
	s_addc_u32 s3, s39, s7
	v_ashrrev_i32_e32 v165, 31, v164
	v_add_u32_e32 v184, 0, v194
	v_add_u32_e32 v185, s50, v194
	v_add_u32_e32 v186, s51, v194
	v_lshl_add_u64 v[164:165], v[164:165], 1, s[2:3]
	v_and_b32_e32 v194, 0x70, v168
	v_lshl_add_u64 v[172:173], v[164:165], 0, v[194:195]
	v_add_co_u32_e32 v174, vcc, s55, v172
	v_readfirstlane_b32 s63, v196
	s_nop 0
	v_addc_co_u32_e32 v175, vcc, 0, v173, vcc
	global_load_dwordx4 v[164:167], v[172:173], off
	global_load_dwordx4 v[168:171], v[174:175], off
	v_add_co_u32_e32 v180, vcc, s56, v172
	v_and_b32_e32 v197, 31, v196
	s_nop 0
	v_addc_co_u32_e32 v181, vcc, 0, v173, vcc
	v_add_co_u32_e32 v182, vcc, s57, v172
	s_bfe_u32 s64, s63, 0x10006
	s_nop 0
	v_addc_co_u32_e32 v183, vcc, 0, v173, vcc
	global_load_dwordx4 v[172:175], v[180:181], off
	global_load_dwordx4 v[176:179], v[182:183], off
	v_readlane_b32 s2, v198, 0
	v_readlane_b32 s3, v198, 1
	v_readlane_b32 s4, v198, 2
	v_readlane_b32 s5, v198, 3
	v_readlane_b32 s6, v198, 4
	v_readlane_b32 s7, v198, 5
	v_readlane_b32 s8, v198, 6
	v_readlane_b32 s9, v198, 7
	v_readlane_b32 s46, v198, 8
	v_readlane_b32 s62, v198, 9
	v_readlane_b32 s63, v198, 10
	v_readlane_b32 s64, v198, 11
	s_nop 3
	s_and_b64 vcc, exec, s[36:37]
	ds_read_b128 v[0:3], v25 offset:17408
	ds_read_b128 v[44:47], v87 offset:8192
	ds_read_b128 v[40:43], v87 offset:8224
	ds_read_b128 v[4:7], v25 offset:17440
	s_waitcnt lgkmcnt(2)
	v_mfma_f32_32x32x16_bf16 v[8:23], v[0:3], v[44:47], 0
	v_lshlrev_b32_e32 v52, 2, v48
	v_or_b32_e32 v84, 2, v52
	v_or_b32_e32 v83, 3, v52
	v_or_b32_e32 v82, 8, v52
	v_or_b32_e32 v81, 9, v52
	v_or_b32_e32 v80, 10, v52
	v_or_b32_e32 v79, 11, v52
	s_waitcnt lgkmcnt(0)
	v_mfma_f32_32x32x16_bf16 v[8:23], v[4:7], v[40:43], v[8:23]
	ds_read_b128 v[0:3], v25 offset:17472
	ds_read_b128 v[36:39], v87 offset:8256
	ds_read_b128 v[32:35], v87 offset:8288
	ds_read_b128 v[4:7], v25 offset:17504
	v_or_b32_e32 v78, 16, v52
	v_or_b32_e32 v77, 17, v52
	v_or_b32_e32 v76, 18, v52
	v_or_b32_e32 v75, 19, v52
	v_or_b32_e32 v74, 24, v52
	v_or_b32_e32 v73, 25, v52
	s_waitcnt lgkmcnt(2)
	v_mfma_f32_32x32x16_bf16 v[8:23], v[0:3], v[36:39], v[8:23]
	v_or_b32_e32 v72, 26, v52
	v_or_b32_e32 v71, 27, v52
	v_cmp_le_u32_e64 s[2:3], v52, v68
	v_cmp_lt_u32_e64 s[4:5], v52, v68
	v_cmp_le_u32_e64 s[6:7], v84, v68
	v_cmp_le_u32_e64 s[8:9], v83, v68
	v_cmp_le_u32_e64 s[10:11], v82, v68
	s_waitcnt lgkmcnt(0)
	v_mfma_f32_32x32x16_bf16 v[8:23], v[4:7], v[32:35], v[8:23]
	v_cmp_le_u32_e64 s[12:13], v81, v68
	v_cmp_le_u32_e64 s[14:15], v80, v68
	v_cmp_le_u32_e64 s[16:17], v79, v68
	v_cmp_le_u32_e64 s[18:19], v78, v68
	v_cmp_le_u32_e64 s[20:21], v77, v68
	v_cmp_le_u32_e64 s[22:23], v76, v68
	v_cmp_le_u32_e64 s[24:25], v75, v68
	v_cmp_le_u32_e64 s[26:27], v74, v68
	v_cmp_le_u32_e64 s[28:29], v73, v68
	v_cmp_le_u32_e64 s[30:31], v72, v68
	v_cmp_le_u32_e64 s[34:35], v71, v68
	s_cbranch_vccnz .LBB0_507
	v_cndmask_b32_e64 v8, 0, v8, s[2:3]
	v_cndmask_b32_e64 v9, 0, v9, s[4:5]
	v_cndmask_b32_e64 v10, 0, v10, s[6:7]
	v_cndmask_b32_e64 v11, 0, v11, s[8:9]
	v_cndmask_b32_e64 v12, 0, v12, s[10:11]
	v_cndmask_b32_e64 v13, 0, v13, s[12:13]
	v_cndmask_b32_e64 v14, 0, v14, s[14:15]
	v_cndmask_b32_e64 v15, 0, v15, s[16:17]
	v_cndmask_b32_e64 v16, 0, v16, s[18:19]
	v_cndmask_b32_e64 v17, 0, v17, s[20:21]
	v_cndmask_b32_e64 v18, 0, v18, s[22:23]
	v_cndmask_b32_e64 v19, 0, v19, s[24:25]
	v_cndmask_b32_e64 v20, 0, v20, s[26:27]
	v_cndmask_b32_e64 v21, 0, v21, s[28:29]
	v_cndmask_b32_e64 v22, 0, v22, s[30:31]
	v_cndmask_b32_e64 v23, 0, v23, s[34:35]
